# as DAB + s_setprio 1 for waves 4-7 only while they run the post-barrier P.V region
# speedup vs baseline: 1.0218x; 1.0218x over previous
; #define SBAR() __builtin_amdgcn_sched_barrier(0)
; template <int D0> __device__ __forceinline__ void pv_one(f32x16& od, int vb, bf16x8 pa0, bf16x8 pa1, bf16x8 pa2, bf16x8 pa3) {
;     const s16x4 l0 = tr_read<v_rd_off(D0, 0, 0)>(vb), h0 = tr_read<v_rd_off(D0, 0, 1)>(vb), l1 = tr_read<v_rd_off(D0, 1, 0)>(vb), h1 = tr_read<v_rd_off(D0, 1, 1)>(vb);
;     const s16x4 l2 = tr_read<v_rd_off(D0, 2, 0)>(vb), h2 = tr_read<v_rd_off(D0, 2, 1)>(vb), l3 = tr_read<v_rd_off(D0, 3, 0)>(vb), h3 = tr_read<v_rd_off(D0, 3, 1)>(vb);
;     asm volatile("s_waitcnt lgkmcnt(0)" ::: "memory"); SBAR();
;     ...
;     od = __builtin_amdgcn_mfma_f32_32x32x16_bf16(pa0, PK(l0, h0), od, 0, 0, 0);
;     od = __builtin_amdgcn_mfma_f32_32x32x16_bf16(pa1, PK(l1, h1), od, 0, 0, 0);
;     od = __builtin_amdgcn_mfma_f32_32x32x16_bf16(pa2, PK(l2, h2), od, 0, 0, 0);
;     od = __builtin_amdgcn_mfma_f32_32x32x16_bf16(pa3, PK(l3, h3), od, 0, 0, 0);
;     ...
; }
; template <bool RSM> __device__ __forceinline__ void pv_d0(f32x16* o, f32x16& lacc, int vb, bf16x8 pa0, bf16x8 pa1, bf16x8 pa2, bf16x8 pa3) {
;     if (RSM) {
;         const bf16x8 ones = {0x3F80, 0x3F80, 0x3F80, 0x3F80, 0x3F80, 0x3F80, 0x3F80, 0x3F80};
;         lacc = __builtin_amdgcn_mfma_f32_32x32x16_bf16(pa0, ones, lacc, 0, 0, 0);
;         lacc = __builtin_amdgcn_mfma_f32_32x32x16_bf16(pa1, ones, lacc, 0, 0, 0);
;         lacc = __builtin_amdgcn_mfma_f32_32x32x16_bf16(pa2, ones, lacc, 0, 0, 0);
;         lacc = __builtin_amdgcn_mfma_f32_32x32x16_bf16(pa3, ones, lacc, 0, 0, 0); }
;     pv_one<0>(o[0], vb, pa0, pa1, pa2, pa3); pv_one<1>(o[1], vb, pa0, pa1, pa2, pa3); pv_one<2>(o[2], vb, pa0, pa1, pa2, pa3); pv_one<3>(o[3], vb, pa0, pa1, pa2, pa3);
.Lmy_r2a_0:
	s_setprio 1
	s_lshl_b32 s19, s16, 14
	v_add_u32_e32 v14, s19, v196
	ds_read_b64_tr_b16 v[100:101], v14 offset:0
	ds_read_b64_tr_b16 v[102:103], v14 offset:0x800
	ds_read_b64_tr_b16 v[104:105], v14 offset:0x1000
	ds_read_b64_tr_b16 v[106:107], v14 offset:0x1800
	ds_read_b64_tr_b16 v[108:109], v14 offset:0x2000
	ds_read_b64_tr_b16 v[110:111], v14 offset:0x2800
	ds_read_b64_tr_b16 v[176:177], v14 offset:0x3000
	ds_read_b64_tr_b16 v[178:179], v14 offset:0x3800
	s_waitcnt lgkmcnt(0)
	s_nop 0
	v_mfma_f32_32x32x16_bf16 v[64:79], v[2:5], v[100:103], v[64:79]
	ds_read_b64_tr_b16 v[100:101], v14 offset:0x200
	ds_read_b64_tr_b16 v[102:103], v14 offset:0xa00
	v_mfma_f32_32x32x16_bf16 v[64:79], v[6:9], v[104:107], v[64:79]
	ds_read_b64_tr_b16 v[104:105], v14 offset:0x1200
	ds_read_b64_tr_b16 v[106:107], v14 offset:0x1a00
	v_mfma_f32_32x32x16_bf16 v[64:79], v[10:13], v[108:111], v[64:79]
	ds_read_b64_tr_b16 v[108:109], v14 offset:0x2200
	ds_read_b64_tr_b16 v[110:111], v14 offset:0x2a00
	v_mfma_f32_32x32x16_bf16 v[64:79], v[96:99], v[176:179], v[64:79]
	ds_read_b64_tr_b16 v[176:177], v14 offset:0x3200
	ds_read_b64_tr_b16 v[178:179], v14 offset:0x3a00
	s_waitcnt lgkmcnt(0)
	v_mfma_f32_32x32x16_bf16 v[48:63], v[2:5], v[100:103], v[48:63]
	ds_read_b64_tr_b16 v[100:101], v14 offset:0x400
	ds_read_b64_tr_b16 v[102:103], v14 offset:0xc00
	v_mfma_f32_32x32x16_bf16 v[48:63], v[6:9], v[104:107], v[48:63]
	ds_read_b64_tr_b16 v[104:105], v14 offset:0x1400
	ds_read_b64_tr_b16 v[106:107], v14 offset:0x1c00
	v_mfma_f32_32x32x16_bf16 v[48:63], v[10:13], v[108:111], v[48:63]
	ds_read_b64_tr_b16 v[108:109], v14 offset:0x2400
	ds_read_b64_tr_b16 v[110:111], v14 offset:0x2c00
	v_mfma_f32_32x32x16_bf16 v[48:63], v[96:99], v[176:179], v[48:63]
	ds_read_b64_tr_b16 v[176:177], v14 offset:0x3400
	ds_read_b64_tr_b16 v[178:179], v14 offset:0x3c00
	s_waitcnt lgkmcnt(0)
	v_mfma_f32_32x32x16_bf16 v[32:47], v[2:5], v[100:103], v[32:47]
	ds_read_b64_tr_b16 v[100:101], v14 offset:0x600
	ds_read_b64_tr_b16 v[102:103], v14 offset:0xe00
	v_mfma_f32_32x32x16_bf16 v[32:47], v[6:9], v[104:107], v[32:47]
	ds_read_b64_tr_b16 v[104:105], v14 offset:0x1600
	ds_read_b64_tr_b16 v[106:107], v14 offset:0x1e00
	v_mfma_f32_32x32x16_bf16 v[32:47], v[10:13], v[108:111], v[32:47]
	ds_read_b64_tr_b16 v[108:109], v14 offset:0x2600
	ds_read_b64_tr_b16 v[110:111], v14 offset:0x2e00
	v_mfma_f32_32x32x16_bf16 v[32:47], v[96:99], v[176:179], v[32:47]
	ds_read_b64_tr_b16 v[176:177], v14 offset:0x3600
	ds_read_b64_tr_b16 v[178:179], v14 offset:0x3e00
	s_waitcnt lgkmcnt(0)
	v_mfma_f32_32x32x16_bf16 v[16:31], v[2:5], v[100:103], v[16:31]
	v_cndmask_b32_e64 v2, 0, 1, s[54:55]
	v_cmp_ne_u32_e64 s[0:1], 1, v2
	s_andn2_b64 vcc, exec, s[54:55]
	v_mfma_f32_32x32x16_bf16 v[16:31], v[6:9], v[104:107], v[16:31]
	v_mfma_f32_32x32x16_bf16 v[16:31], v[10:13], v[108:111], v[16:31]
	v_mfma_f32_32x32x16_bf16 v[16:31], v[96:99], v[176:179], v[16:31]
	s_setprio 0
	s_add_i32 s6, s81, s13
	s_mov_b32 m0, s6
	v_lshl_add_u64 v[14:15], v[186:187], 0, s[74:75]
	global_load_lds_dwordx4 v[184:185], off
	s_add_i32 m0, s6, 0x2000
	s_lshl_b32 s6, s16, 14
	s_addk_i32 s6, 0xc000
	s_cmp_gt_i32 s16, 0
	s_cselect_b32 s6, s6, 0xc000
	s_add_i32 s6, s63, s6
	global_load_lds_dwordx4 v[188:189], off
	s_mov_b32 m0, s6
	v_lshl_add_u64 v[184:185], v[184:185], 0, s[74:75]
	global_load_lds_dwordx4 v[186:187], off
	s_add_i32 m0, s6, 0x2000
	v_lshl_add_u64 v[188:189], v[188:189], 0, s[74:75]
	global_load_lds_dwordx4 v[190:191], off
	v_lshl_add_u64 v[100:101], v[190:191], 0, s[74:75]
	v_mov_b64_e32 v[190:191], v[100:101]
	v_mov_b64_e32 v[186:187], v[14:15]
	s_cbranch_vccnz .LBB0_395
	s_branch .Lmy_fta_0
; #define SBAR() __builtin_amdgcn_sched_barrier(0)
; template <int D0> __device__ __forceinline__ void pv_one(f32x16& od, int vb, bf16x8 pa0, bf16x8 pa1, bf16x8 pa2, bf16x8 pa3) {
;     const s16x4 l0 = tr_read<v_rd_off(D0, 0, 0)>(vb), h0 = tr_read<v_rd_off(D0, 0, 1)>(vb), l1 = tr_read<v_rd_off(D0, 1, 0)>(vb), h1 = tr_read<v_rd_off(D0, 1, 1)>(vb);
;     const s16x4 l2 = tr_read<v_rd_off(D0, 2, 0)>(vb), h2 = tr_read<v_rd_off(D0, 2, 1)>(vb), l3 = tr_read<v_rd_off(D0, 3, 0)>(vb), h3 = tr_read<v_rd_off(D0, 3, 1)>(vb);
;     asm volatile("s_waitcnt lgkmcnt(0)" ::: "memory"); SBAR();
;     ...
;     od = __builtin_amdgcn_mfma_f32_32x32x16_bf16(pa0, PK(l0, h0), od, 0, 0, 0);
;     od = __builtin_amdgcn_mfma_f32_32x32x16_bf16(pa1, PK(l1, h1), od, 0, 0, 0);
;     od = __builtin_amdgcn_mfma_f32_32x32x16_bf16(pa2, PK(l2, h2), od, 0, 0, 0);
;     od = __builtin_amdgcn_mfma_f32_32x32x16_bf16(pa3, PK(l3, h3), od, 0, 0, 0);
;     ...
; }
; template <bool RSM> __device__ __forceinline__ void pv_d0(f32x16* o, f32x16& lacc, int vb, bf16x8 pa0, bf16x8 pa1, bf16x8 pa2, bf16x8 pa3) {
;     if (RSM) {
;         const bf16x8 ones = {0x3F80, 0x3F80, 0x3F80, 0x3F80, 0x3F80, 0x3F80, 0x3F80, 0x3F80};
;         lacc = __builtin_amdgcn_mfma_f32_32x32x16_bf16(pa0, ones, lacc, 0, 0, 0);
;         lacc = __builtin_amdgcn_mfma_f32_32x32x16_bf16(pa1, ones, lacc, 0, 0, 0);
;         lacc = __builtin_amdgcn_mfma_f32_32x32x16_bf16(pa2, ones, lacc, 0, 0, 0);
;         lacc = __builtin_amdgcn_mfma_f32_32x32x16_bf16(pa3, ones, lacc, 0, 0, 0); }
;     pv_one<0>(o[0], vb, pa0, pa1, pa2, pa3); pv_one<1>(o[1], vb, pa0, pa1, pa2, pa3); pv_one<2>(o[2], vb, pa0, pa1, pa2, pa3); pv_one<3>(o[3], vb, pa0, pa1, pa2, pa3);
.Lmy_r2a_1:
	s_setprio 1
	s_lshl_b32 s12, s13, 14
	v_add_u32_e32 v117, s12, v196
	ds_read_b64_tr_b16 v[118:119], v117 offset:0
	ds_read_b64_tr_b16 v[120:121], v117 offset:0x800
	ds_read_b64_tr_b16 v[122:123], v117 offset:0x1000
	ds_read_b64_tr_b16 v[124:125], v117 offset:0x1800
	ds_read_b64_tr_b16 v[176:177], v117 offset:0x2000
	ds_read_b64_tr_b16 v[178:179], v117 offset:0x2800
	ds_read_b64_tr_b16 v[180:181], v117 offset:0x3000
	ds_read_b64_tr_b16 v[182:183], v117 offset:0x3800
	s_waitcnt lgkmcnt(0)
	s_nop 0
	v_mfma_f32_32x32x16_bf16 v[64:79], v[2:5], v[118:121], v[64:79]
	ds_read_b64_tr_b16 v[118:119], v117 offset:0x200
	ds_read_b64_tr_b16 v[120:121], v117 offset:0xa00
	v_mfma_f32_32x32x16_bf16 v[64:79], v[6:9], v[122:125], v[64:79]
	ds_read_b64_tr_b16 v[122:123], v117 offset:0x1200
	ds_read_b64_tr_b16 v[124:125], v117 offset:0x1a00
	v_mfma_f32_32x32x16_bf16 v[64:79], v[10:13], v[176:179], v[64:79]
	ds_read_b64_tr_b16 v[176:177], v117 offset:0x2200
	ds_read_b64_tr_b16 v[178:179], v117 offset:0x2a00
	v_mfma_f32_32x32x16_bf16 v[64:79], v[112:115], v[180:183], v[64:79]
	ds_read_b64_tr_b16 v[180:181], v117 offset:0x3200
	ds_read_b64_tr_b16 v[182:183], v117 offset:0x3a00
	s_waitcnt lgkmcnt(0)
	v_mfma_f32_32x32x16_bf16 v[48:63], v[2:5], v[118:121], v[48:63]
	ds_read_b64_tr_b16 v[118:119], v117 offset:0x400
	ds_read_b64_tr_b16 v[120:121], v117 offset:0xc00
	v_mfma_f32_32x32x16_bf16 v[48:63], v[6:9], v[122:125], v[48:63]
	ds_read_b64_tr_b16 v[122:123], v117 offset:0x1400
	ds_read_b64_tr_b16 v[124:125], v117 offset:0x1c00
	v_mfma_f32_32x32x16_bf16 v[48:63], v[10:13], v[176:179], v[48:63]
	ds_read_b64_tr_b16 v[176:177], v117 offset:0x2400
	ds_read_b64_tr_b16 v[178:179], v117 offset:0x2c00
	v_mfma_f32_32x32x16_bf16 v[48:63], v[112:115], v[180:183], v[48:63]
	ds_read_b64_tr_b16 v[180:181], v117 offset:0x3400
	ds_read_b64_tr_b16 v[182:183], v117 offset:0x3c00
	s_waitcnt lgkmcnt(0)
	v_mfma_f32_32x32x16_bf16 v[32:47], v[2:5], v[118:121], v[32:47]
	ds_read_b64_tr_b16 v[118:119], v117 offset:0x600
	ds_read_b64_tr_b16 v[120:121], v117 offset:0xe00
	v_mfma_f32_32x32x16_bf16 v[32:47], v[6:9], v[122:125], v[32:47]
	ds_read_b64_tr_b16 v[122:123], v117 offset:0x1600
	ds_read_b64_tr_b16 v[124:125], v117 offset:0x1e00
	v_mfma_f32_32x32x16_bf16 v[32:47], v[10:13], v[176:179], v[32:47]
	ds_read_b64_tr_b16 v[176:177], v117 offset:0x2600
	ds_read_b64_tr_b16 v[178:179], v117 offset:0x2e00
	v_mfma_f32_32x32x16_bf16 v[32:47], v[112:115], v[180:183], v[32:47]
	ds_read_b64_tr_b16 v[180:181], v117 offset:0x3600
	ds_read_b64_tr_b16 v[182:183], v117 offset:0x3e00
	s_waitcnt lgkmcnt(0)
	v_mfma_f32_32x32x16_bf16 v[16:31], v[2:5], v[118:121], v[16:31]
	s_and_b64 vcc, exec, s[0:1]
	v_mfma_f32_32x32x16_bf16 v[16:31], v[6:9], v[122:125], v[16:31]
	v_mfma_f32_32x32x16_bf16 v[16:31], v[10:13], v[176:179], v[16:31]
	v_mfma_f32_32x32x16_bf16 v[16:31], v[112:115], v[180:183], v[16:31]
	s_setprio 0
	s_mov_b32 m0, s6
	s_nop 0
	global_load_lds_dwordx4 v[184:185], off
	s_add_i32 m0, s6, 0x2000
	s_lshl_b32 s6, s13, 14
	s_addk_i32 s6, 0xc000
	s_cmp_gt_i32 s13, 0
	s_cselect_b32 s6, s6, 0xc000
	s_add_i32 s6, s63, s6
	global_load_lds_dwordx4 v[188:189], off
	s_mov_b32 m0, s6
	v_lshl_add_u64 v[184:185], v[184:185], 0, s[74:75]
	global_load_lds_dwordx4 v[186:187], off
	s_add_i32 m0, s6, 0x2000
	v_lshl_add_u64 v[188:189], v[188:189], 0, s[74:75]
	global_load_lds_dwordx4 v[190:191], off
	v_lshl_add_u64 v[186:187], v[186:187], 0, s[74:75]
	v_lshl_add_u64 v[190:191], v[190:191], 0, s[74:75]
	s_cbranch_vccnz .LBB0_406
	s_branch .Lmy_fta_1

; #define SBAR() __builtin_amdgcn_sched_barrier(0)
; template <int D0> __device__ __forceinline__ void pv_one(f32x16& od, int vb, bf16x8 pa0, bf16x8 pa1, bf16x8 pa2, bf16x8 pa3) {
;     const s16x4 l0 = tr_read<v_rd_off(D0, 0, 0)>(vb), h0 = tr_read<v_rd_off(D0, 0, 1)>(vb), l1 = tr_read<v_rd_off(D0, 1, 0)>(vb), h1 = tr_read<v_rd_off(D0, 1, 1)>(vb);
;     const s16x4 l2 = tr_read<v_rd_off(D0, 2, 0)>(vb), h2 = tr_read<v_rd_off(D0, 2, 1)>(vb), l3 = tr_read<v_rd_off(D0, 3, 0)>(vb), h3 = tr_read<v_rd_off(D0, 3, 1)>(vb);
;     asm volatile("s_waitcnt lgkmcnt(0)" ::: "memory"); SBAR();
;     ...
;     od = __builtin_amdgcn_mfma_f32_32x32x16_bf16(pa0, PK(l0, h0), od, 0, 0, 0);
;     od = __builtin_amdgcn_mfma_f32_32x32x16_bf16(pa1, PK(l1, h1), od, 0, 0, 0);
;     od = __builtin_amdgcn_mfma_f32_32x32x16_bf16(pa2, PK(l2, h2), od, 0, 0, 0);
;     od = __builtin_amdgcn_mfma_f32_32x32x16_bf16(pa3, PK(l3, h3), od, 0, 0, 0);
;     ...
; }
; template <bool RSM> __device__ __forceinline__ void pv_d0(f32x16* o, f32x16& lacc, int vb, bf16x8 pa0, bf16x8 pa1, bf16x8 pa2, bf16x8 pa3) {
;     if (RSM) {
;         const bf16x8 ones = {0x3F80, 0x3F80, 0x3F80, 0x3F80, 0x3F80, 0x3F80, 0x3F80, 0x3F80};
;         lacc = __builtin_amdgcn_mfma_f32_32x32x16_bf16(pa0, ones, lacc, 0, 0, 0);
;         lacc = __builtin_amdgcn_mfma_f32_32x32x16_bf16(pa1, ones, lacc, 0, 0, 0);
;         lacc = __builtin_amdgcn_mfma_f32_32x32x16_bf16(pa2, ones, lacc, 0, 0, 0);
;         lacc = __builtin_amdgcn_mfma_f32_32x32x16_bf16(pa3, ones, lacc, 0, 0, 0); }
;     pv_one<0>(o[0], vb, pa0, pa1, pa2, pa3); pv_one<1>(o[1], vb, pa0, pa1, pa2, pa3); pv_one<2>(o[2], vb, pa0, pa1, pa2, pa3); pv_one<3>(o[3], vb, pa0, pa1, pa2, pa3);
.Lmy_r2b_0:
	s_setprio 1
	s_lshl_b32 s18, s12, 14
	v_add_u32_e32 v197, s18, v177
	ds_read_b64_tr_b16 v[172:173], v197 offset:0
	ds_read_b64_tr_b16 v[174:175], v197 offset:0x800
	ds_read_b64_tr_b16 v[198:199], v197 offset:0x1000
	ds_read_b64_tr_b16 v[200:201], v197 offset:0x1800
	ds_read_b64_tr_b16 v[208:209], v197 offset:0x2000
	ds_read_b64_tr_b16 v[210:211], v197 offset:0x2800
	ds_read_b64_tr_b16 v[212:213], v197 offset:0x3000
	ds_read_b64_tr_b16 v[214:215], v197 offset:0x3800
	s_waitcnt lgkmcnt(0)
	s_nop 0
	v_mfma_f32_32x32x16_bf16 v[50:65], v[146:149], v[172:175], v[50:65]
	ds_read_b64_tr_b16 v[172:173], v197 offset:0x200
	ds_read_b64_tr_b16 v[174:175], v197 offset:0xa00
	v_mfma_f32_32x32x16_bf16 v[50:65], v[150:153], v[198:201], v[50:65]
	ds_read_b64_tr_b16 v[198:199], v197 offset:0x1200
	ds_read_b64_tr_b16 v[200:201], v197 offset:0x1a00
	v_mfma_f32_32x32x16_bf16 v[50:65], v[154:157], v[208:211], v[50:65]
	ds_read_b64_tr_b16 v[208:209], v197 offset:0x2200
	ds_read_b64_tr_b16 v[210:211], v197 offset:0x2a00
	v_mfma_f32_32x32x16_bf16 v[50:65], v[158:161], v[212:215], v[50:65]
	ds_read_b64_tr_b16 v[212:213], v197 offset:0x3200
	ds_read_b64_tr_b16 v[214:215], v197 offset:0x3a00
	s_waitcnt lgkmcnt(0)
	v_mfma_f32_32x32x16_bf16 v[34:49], v[146:149], v[172:175], v[34:49]
	ds_read_b64_tr_b16 v[172:173], v197 offset:0x400
	ds_read_b64_tr_b16 v[174:175], v197 offset:0xc00
	v_mfma_f32_32x32x16_bf16 v[34:49], v[150:153], v[198:201], v[34:49]
	ds_read_b64_tr_b16 v[198:199], v197 offset:0x1400
	ds_read_b64_tr_b16 v[200:201], v197 offset:0x1c00
	v_mfma_f32_32x32x16_bf16 v[34:49], v[154:157], v[208:211], v[34:49]
	ds_read_b64_tr_b16 v[208:209], v197 offset:0x2400
	ds_read_b64_tr_b16 v[210:211], v197 offset:0x2c00
	v_mfma_f32_32x32x16_bf16 v[34:49], v[158:161], v[212:215], v[34:49]
	ds_read_b64_tr_b16 v[212:213], v197 offset:0x3400
	ds_read_b64_tr_b16 v[214:215], v197 offset:0x3c00
	s_waitcnt lgkmcnt(0)
	v_mfma_f32_32x32x16_bf16 v[18:33], v[146:149], v[172:175], v[18:33]
	ds_read_b64_tr_b16 v[172:173], v197 offset:0x600
	ds_read_b64_tr_b16 v[174:175], v197 offset:0xe00
	v_mfma_f32_32x32x16_bf16 v[18:33], v[150:153], v[198:201], v[18:33]
	ds_read_b64_tr_b16 v[198:199], v197 offset:0x1600
	ds_read_b64_tr_b16 v[200:201], v197 offset:0x1e00
	v_mfma_f32_32x32x16_bf16 v[18:33], v[154:157], v[208:211], v[18:33]
	ds_read_b64_tr_b16 v[208:209], v197 offset:0x2600
	ds_read_b64_tr_b16 v[210:211], v197 offset:0x2e00
	v_mfma_f32_32x32x16_bf16 v[18:33], v[158:161], v[212:215], v[18:33]
	ds_read_b64_tr_b16 v[212:213], v197 offset:0x3600
	ds_read_b64_tr_b16 v[214:215], v197 offset:0x3e00
	s_waitcnt lgkmcnt(0)
	v_mfma_f32_32x32x16_bf16 v[2:17], v[146:149], v[172:175], v[2:17]
	s_and_b64 vcc, exec, s[0:1]
	v_mfma_f32_32x32x16_bf16 v[2:17], v[150:153], v[198:201], v[2:17]
	v_mfma_f32_32x32x16_bf16 v[2:17], v[154:157], v[208:211], v[2:17]
	v_mfma_f32_32x32x16_bf16 v[2:17], v[158:161], v[212:215], v[2:17]
	s_setprio 0
	s_mov_b32 m0, s14
	v_lshl_add_u64 v[172:173], v[170:171], 0, s[94:95]
	global_load_lds_dwordx4 v[162:163], off
	s_add_i32 m0, s14, 0x2000
	v_lshl_add_u64 v[162:163], v[162:163], 0, s[94:95]
	global_load_lds_dwordx4 v[164:165], off
	s_add_i32 m0, s14, 0x4000
	s_lshl_b32 s14, s12, 14
	s_addk_i32 s14, 0xc000
	s_cmp_gt_i32 s12, 0
	s_cselect_b32 s14, s14, 0xc000
	s_add_i32 s14, s63, s14
	global_load_lds_dwordx4 v[166:167], off
	s_mov_b32 m0, s14
	v_lshl_add_u64 v[164:165], v[164:165], 0, s[94:95]
	global_load_lds_dwordx4 v[170:171], off
	s_add_i32 m0, s14, 0x2000
	v_lshl_add_u64 v[166:167], v[166:167], 0, s[74:75]
	global_load_lds_dwordx4 v[168:169], off
	v_lshl_add_u64 v[174:175], v[168:169], 0, s[94:95]
	v_mov_b64_e32 v[168:169], v[174:175]
	v_mov_b64_e32 v[170:171], v[172:173]
	s_cbranch_vccnz .LBB0_449
	s_branch .Lmy_ftb_0
; #define SBAR() __builtin_amdgcn_sched_barrier(0)
; template <int D0> __device__ __forceinline__ void pv_one(f32x16& od, int vb, bf16x8 pa0, bf16x8 pa1, bf16x8 pa2, bf16x8 pa3) {
;     const s16x4 l0 = tr_read<v_rd_off(D0, 0, 0)>(vb), h0 = tr_read<v_rd_off(D0, 0, 1)>(vb), l1 = tr_read<v_rd_off(D0, 1, 0)>(vb), h1 = tr_read<v_rd_off(D0, 1, 1)>(vb);
;     const s16x4 l2 = tr_read<v_rd_off(D0, 2, 0)>(vb), h2 = tr_read<v_rd_off(D0, 2, 1)>(vb), l3 = tr_read<v_rd_off(D0, 3, 0)>(vb), h3 = tr_read<v_rd_off(D0, 3, 1)>(vb);
;     asm volatile("s_waitcnt lgkmcnt(0)" ::: "memory"); SBAR();
;     ...
;     od = __builtin_amdgcn_mfma_f32_32x32x16_bf16(pa0, PK(l0, h0), od, 0, 0, 0);
;     od = __builtin_amdgcn_mfma_f32_32x32x16_bf16(pa1, PK(l1, h1), od, 0, 0, 0);
;     od = __builtin_amdgcn_mfma_f32_32x32x16_bf16(pa2, PK(l2, h2), od, 0, 0, 0);
;     od = __builtin_amdgcn_mfma_f32_32x32x16_bf16(pa3, PK(l3, h3), od, 0, 0, 0);
;     ...
; }
; template <bool RSM> __device__ __forceinline__ void pv_d0(f32x16* o, f32x16& lacc, int vb, bf16x8 pa0, bf16x8 pa1, bf16x8 pa2, bf16x8 pa3) {
;     if (RSM) {
;         const bf16x8 ones = {0x3F80, 0x3F80, 0x3F80, 0x3F80, 0x3F80, 0x3F80, 0x3F80, 0x3F80};
;         lacc = __builtin_amdgcn_mfma_f32_32x32x16_bf16(pa0, ones, lacc, 0, 0, 0);
;         lacc = __builtin_amdgcn_mfma_f32_32x32x16_bf16(pa1, ones, lacc, 0, 0, 0);
;         lacc = __builtin_amdgcn_mfma_f32_32x32x16_bf16(pa2, ones, lacc, 0, 0, 0);
;         lacc = __builtin_amdgcn_mfma_f32_32x32x16_bf16(pa3, ones, lacc, 0, 0, 0); }
;     pv_one<0>(o[0], vb, pa0, pa1, pa2, pa3); pv_one<1>(o[1], vb, pa0, pa1, pa2, pa3); pv_one<2>(o[2], vb, pa0, pa1, pa2, pa3); pv_one<3>(o[3], vb, pa0, pa1, pa2, pa3);
.Lmy_r2b_1:
	s_setprio 1
	s_lshl_b32 s19, s15, 14
	v_add_u32_e32 v175, s19, v177
	ds_read_b64_tr_b16 v[198:199], v175 offset:0
	ds_read_b64_tr_b16 v[200:201], v175 offset:0x800
	ds_read_b64_tr_b16 v[208:209], v175 offset:0x1000
	ds_read_b64_tr_b16 v[210:211], v175 offset:0x1800
	ds_read_b64_tr_b16 v[212:213], v175 offset:0x2000
	ds_read_b64_tr_b16 v[214:215], v175 offset:0x2800
	ds_read_b64_tr_b16 v[226:227], v175 offset:0x3000
	ds_read_b64_tr_b16 v[228:229], v175 offset:0x3800
	s_waitcnt lgkmcnt(0)
	s_nop 0
	v_mfma_f32_32x32x16_bf16 v[50:65], v[146:149], v[198:201], v[50:65]
	ds_read_b64_tr_b16 v[198:199], v175 offset:0x200
	ds_read_b64_tr_b16 v[200:201], v175 offset:0xa00
	v_mfma_f32_32x32x16_bf16 v[50:65], v[150:153], v[208:211], v[50:65]
	ds_read_b64_tr_b16 v[208:209], v175 offset:0x1200
	ds_read_b64_tr_b16 v[210:211], v175 offset:0x1a00
	v_mfma_f32_32x32x16_bf16 v[50:65], v[154:157], v[212:215], v[50:65]
	ds_read_b64_tr_b16 v[212:213], v175 offset:0x2200
	ds_read_b64_tr_b16 v[214:215], v175 offset:0x2a00
	v_mfma_f32_32x32x16_bf16 v[50:65], v[158:161], v[226:229], v[50:65]
	ds_read_b64_tr_b16 v[226:227], v175 offset:0x3200
	ds_read_b64_tr_b16 v[228:229], v175 offset:0x3a00
	s_waitcnt lgkmcnt(0)
	v_mfma_f32_32x32x16_bf16 v[34:49], v[146:149], v[198:201], v[34:49]
	ds_read_b64_tr_b16 v[198:199], v175 offset:0x400
	ds_read_b64_tr_b16 v[200:201], v175 offset:0xc00
	v_mfma_f32_32x32x16_bf16 v[34:49], v[150:153], v[208:211], v[34:49]
	ds_read_b64_tr_b16 v[208:209], v175 offset:0x1400
	ds_read_b64_tr_b16 v[210:211], v175 offset:0x1c00
	v_mfma_f32_32x32x16_bf16 v[34:49], v[154:157], v[212:215], v[34:49]
	ds_read_b64_tr_b16 v[212:213], v175 offset:0x2400
	ds_read_b64_tr_b16 v[214:215], v175 offset:0x2c00
	v_mfma_f32_32x32x16_bf16 v[34:49], v[158:161], v[226:229], v[34:49]
	ds_read_b64_tr_b16 v[226:227], v175 offset:0x3400
	ds_read_b64_tr_b16 v[228:229], v175 offset:0x3c00
	s_waitcnt lgkmcnt(0)
	v_mfma_f32_32x32x16_bf16 v[18:33], v[146:149], v[198:201], v[18:33]
	ds_read_b64_tr_b16 v[198:199], v175 offset:0x600
	ds_read_b64_tr_b16 v[200:201], v175 offset:0xe00
	v_mfma_f32_32x32x16_bf16 v[18:33], v[150:153], v[208:211], v[18:33]
	ds_read_b64_tr_b16 v[208:209], v175 offset:0x1600
	ds_read_b64_tr_b16 v[210:211], v175 offset:0x1e00
	v_mfma_f32_32x32x16_bf16 v[18:33], v[154:157], v[212:215], v[18:33]
	ds_read_b64_tr_b16 v[212:213], v175 offset:0x2600
	ds_read_b64_tr_b16 v[214:215], v175 offset:0x2e00
	v_mfma_f32_32x32x16_bf16 v[18:33], v[158:161], v[226:229], v[18:33]
	ds_read_b64_tr_b16 v[226:227], v175 offset:0x3600
	ds_read_b64_tr_b16 v[228:229], v175 offset:0x3e00
	s_waitcnt lgkmcnt(0)
	v_mfma_f32_32x32x16_bf16 v[2:17], v[146:149], v[198:201], v[2:17]
	s_and_b64 vcc, exec, s[0:1]
	v_mfma_f32_32x32x16_bf16 v[2:17], v[150:153], v[208:211], v[2:17]
	v_mfma_f32_32x32x16_bf16 v[2:17], v[154:157], v[212:215], v[2:17]
	v_mfma_f32_32x32x16_bf16 v[2:17], v[158:161], v[226:229], v[2:17]
	s_setprio 0
	s_mov_b32 m0, s12
	s_nop 0
	global_load_lds_dwordx4 v[162:163], off
	s_add_i32 m0, s12, 0x2000
	v_lshl_add_u64 v[162:163], v[162:163], 0, s[94:95]
	global_load_lds_dwordx4 v[164:165], off
	s_add_i32 m0, s12, 0x4000
	s_lshl_b32 s12, s15, 14
	s_addk_i32 s12, 0xc000
	s_cmp_gt_i32 s15, 0
	s_cselect_b32 s12, s12, 0xc000
	s_add_i32 s12, s63, s12
	global_load_lds_dwordx4 v[166:167], off
	s_mov_b32 m0, s12
	v_lshl_add_u64 v[164:165], v[164:165], 0, s[94:95]
	global_load_lds_dwordx4 v[170:171], off
	s_add_i32 m0, s12, 0x2000
	v_lshl_add_u64 v[166:167], v[166:167], 0, s[74:75]
	global_load_lds_dwordx4 v[168:169], off
	v_lshl_add_u64 v[170:171], v[170:171], 0, s[94:95]
	v_lshl_add_u64 v[168:169], v[168:169], 0, s[94:95]
	s_cbranch_vccnz .LBB0_459
	s_branch .Lmy_ftb_1

; #define SBAR() __builtin_amdgcn_sched_barrier(0)
; template <int D0> __device__ __forceinline__ void pv_one(f32x16& od, int vb, bf16x8 pa0, bf16x8 pa1, bf16x8 pa2, bf16x8 pa3) {
;     const s16x4 l0 = tr_read<v_rd_off(D0, 0, 0)>(vb), h0 = tr_read<v_rd_off(D0, 0, 1)>(vb), l1 = tr_read<v_rd_off(D0, 1, 0)>(vb), h1 = tr_read<v_rd_off(D0, 1, 1)>(vb);
;     const s16x4 l2 = tr_read<v_rd_off(D0, 2, 0)>(vb), h2 = tr_read<v_rd_off(D0, 2, 1)>(vb), l3 = tr_read<v_rd_off(D0, 3, 0)>(vb), h3 = tr_read<v_rd_off(D0, 3, 1)>(vb);
;     asm volatile("s_waitcnt lgkmcnt(0)" ::: "memory"); SBAR();
;     ...
;     od = __builtin_amdgcn_mfma_f32_32x32x16_bf16(pa0, PK(l0, h0), od, 0, 0, 0);
;     od = __builtin_amdgcn_mfma_f32_32x32x16_bf16(pa1, PK(l1, h1), od, 0, 0, 0);
;     od = __builtin_amdgcn_mfma_f32_32x32x16_bf16(pa2, PK(l2, h2), od, 0, 0, 0);
;     od = __builtin_amdgcn_mfma_f32_32x32x16_bf16(pa3, PK(l3, h3), od, 0, 0, 0);
;     ...
; }
; template <bool RSM> __device__ __forceinline__ void pv_d0(f32x16* o, f32x16& lacc, int vb, bf16x8 pa0, bf16x8 pa1, bf16x8 pa2, bf16x8 pa3) {
;     if (RSM) {
;         const bf16x8 ones = {0x3F80, 0x3F80, 0x3F80, 0x3F80, 0x3F80, 0x3F80, 0x3F80, 0x3F80};
;         lacc = __builtin_amdgcn_mfma_f32_32x32x16_bf16(pa0, ones, lacc, 0, 0, 0);
;         lacc = __builtin_amdgcn_mfma_f32_32x32x16_bf16(pa1, ones, lacc, 0, 0, 0);
;         lacc = __builtin_amdgcn_mfma_f32_32x32x16_bf16(pa2, ones, lacc, 0, 0, 0);
;         lacc = __builtin_amdgcn_mfma_f32_32x32x16_bf16(pa3, ones, lacc, 0, 0, 0); }
;     pv_one<0>(o[0], vb, pa0, pa1, pa2, pa3); pv_one<1>(o[1], vb, pa0, pa1, pa2, pa3); pv_one<2>(o[2], vb, pa0, pa1, pa2, pa3); pv_one<3>(o[3], vb, pa0, pa1, pa2, pa3);
; }
.Lmy_r2d_0:
	s_setprio 1
	s_mov_b32 s38, s36
	s_mov_b32 s39, s36
	s_mov_b32 s37, s36
	v_mov_b64_e32 v[134:135], s[38:39]
	v_mov_b64_e32 v[132:133], s[36:37]
	s_lshl_b32 s23, s35, 14
	v_add_u32_e32 v0, s23, v230
	v_mfma_f32_32x32x16_bf16 v[96:111], v[6:9], v[132:135], v[96:111]
	ds_read_b64_tr_b16 v[136:137], v0 offset:0
	ds_read_b64_tr_b16 v[138:139], v0 offset:0x800
	ds_read_b64_tr_b16 v[140:141], v0 offset:0x1000
	ds_read_b64_tr_b16 v[142:143], v0 offset:0x1800
	ds_read_b64_tr_b16 v[192:193], v0 offset:0x2000
	ds_read_b64_tr_b16 v[194:195], v0 offset:0x2800
	ds_read_b64_tr_b16 v[196:197], v0 offset:0x3000
	v_mfma_f32_32x32x16_bf16 v[96:111], v[2:5], v[132:135], v[96:111]
	ds_read_b64_tr_b16 v[198:199], v0 offset:0x3800
	s_waitcnt lgkmcnt(0)
	v_mfma_f32_32x32x16_bf16 v[96:111], v[128:131], v[132:135], v[96:111]
	v_mfma_f32_32x32x16_bf16 v[96:111], v[10:13], v[132:135], v[96:111]
	v_mfma_f32_32x32x16_bf16 v[80:95], v[6:9], v[136:139], v[80:95]
	ds_read_b64_tr_b16 v[132:133], v0 offset:0x200
	ds_read_b64_tr_b16 v[134:135], v0 offset:0xa00
	ds_read_b64_tr_b16 v[136:137], v0 offset:0x1200
	ds_read_b64_tr_b16 v[138:139], v0 offset:0x1a00
	v_mfma_f32_32x32x16_bf16 v[80:95], v[2:5], v[140:143], v[80:95]
	ds_read_b64_tr_b16 v[140:141], v0 offset:0x2200
	ds_read_b64_tr_b16 v[142:143], v0 offset:0x2a00
	v_mfma_f32_32x32x16_bf16 v[80:95], v[128:131], v[192:195], v[80:95]
	ds_read_b64_tr_b16 v[192:193], v0 offset:0x3200
	ds_read_b64_tr_b16 v[194:195], v0 offset:0x3a00
	s_waitcnt lgkmcnt(0)
	v_mfma_f32_32x32x16_bf16 v[80:95], v[10:13], v[196:199], v[80:95]
	v_mfma_f32_32x32x16_bf16 v[64:79], v[6:9], v[132:135], v[64:79]
	ds_read_b64_tr_b16 v[132:133], v0 offset:0x400
	ds_read_b64_tr_b16 v[134:135], v0 offset:0xc00
	v_mfma_f32_32x32x16_bf16 v[64:79], v[2:5], v[136:139], v[64:79]
	ds_read_b64_tr_b16 v[136:137], v0 offset:0x1400
	ds_read_b64_tr_b16 v[138:139], v0 offset:0x1c00
	v_mfma_f32_32x32x16_bf16 v[64:79], v[128:131], v[140:143], v[64:79]
	ds_read_b64_tr_b16 v[140:141], v0 offset:0x2400
	ds_read_b64_tr_b16 v[142:143], v0 offset:0x2c00
	v_mfma_f32_32x32x16_bf16 v[64:79], v[10:13], v[192:195], v[64:79]
	ds_read_b64_tr_b16 v[192:193], v0 offset:0x3400
	ds_read_b64_tr_b16 v[194:195], v0 offset:0x3c00
	s_waitcnt lgkmcnt(0)
	v_mfma_f32_32x32x16_bf16 v[48:63], v[6:9], v[132:135], v[48:63]
	ds_read_b64_tr_b16 v[132:133], v0 offset:0x600
	ds_read_b64_tr_b16 v[134:135], v0 offset:0xe00
	v_mfma_f32_32x32x16_bf16 v[48:63], v[2:5], v[136:139], v[48:63]
	ds_read_b64_tr_b16 v[136:137], v0 offset:0x1600
	ds_read_b64_tr_b16 v[138:139], v0 offset:0x1e00
	v_mfma_f32_32x32x16_bf16 v[48:63], v[128:131], v[140:143], v[48:63]
	ds_read_b64_tr_b16 v[140:141], v0 offset:0x2600
	ds_read_b64_tr_b16 v[142:143], v0 offset:0x2e00
	v_mfma_f32_32x32x16_bf16 v[48:63], v[10:13], v[192:195], v[48:63]
	ds_read_b64_tr_b16 v[192:193], v0 offset:0x3600
	ds_read_b64_tr_b16 v[194:195], v0 offset:0x3e00
	s_waitcnt lgkmcnt(0)
	v_mfma_f32_32x32x16_bf16 v[32:47], v[6:9], v[132:135], v[32:47]
	s_and_b64 vcc, exec, s[0:1]
	v_mfma_f32_32x32x16_bf16 v[32:47], v[2:5], v[136:139], v[32:47]
	v_mfma_f32_32x32x16_bf16 v[32:47], v[128:131], v[140:143], v[32:47]
	v_mfma_f32_32x32x16_bf16 v[32:47], v[10:13], v[192:195], v[32:47]
	s_setprio 0
	global_load_lds_dwordx4 v[214:215], off
	v_lshl_add_u64 v[214:215], v[214:215], 0, s[74:75]
	s_mov_b32 m0, s20
	s_nop 0
	global_load_lds_dwordx4 v[212:213], off
	v_lshl_add_u64 v[212:213], v[212:213], 0, s[74:75]
	s_add_i32 m0, s20, 0x2000
	s_nop 0
	global_load_lds_dwordx4 v[216:217], off
	v_lshl_add_u64 v[216:217], v[216:217], 0, s[74:75]
	s_cbranch_vccnz .LBB0_709
	s_branch .Lmy_r2ft_0
.Lmy_r2d_1:
	s_setprio 1
	s_mov_b32 s38, s36
	s_mov_b32 s39, s36
	s_mov_b32 s37, s36
	v_mov_b64_e32 v[150:151], s[38:39]
	v_mov_b64_e32 v[148:149], s[36:37]
	s_lshl_b32 s37, s35, 14
	v_add_u32_e32 v14, s37, v230
	v_mfma_f32_32x32x16_bf16 v[96:111], v[6:9], v[148:151], v[96:111]
	ds_read_b64_tr_b16 v[152:153], v14 offset:0
	ds_read_b64_tr_b16 v[154:155], v14 offset:0x800
	ds_read_b64_tr_b16 v[156:157], v14 offset:0x1000
	ds_read_b64_tr_b16 v[158:159], v14 offset:0x1800
	ds_read_b64_tr_b16 v[192:193], v14 offset:0x2000
	ds_read_b64_tr_b16 v[194:195], v14 offset:0x2800
	ds_read_b64_tr_b16 v[196:197], v14 offset:0x3000
	v_mfma_f32_32x32x16_bf16 v[96:111], v[2:5], v[148:151], v[96:111]
	ds_read_b64_tr_b16 v[198:199], v14 offset:0x3800
	s_waitcnt lgkmcnt(0)
	v_mfma_f32_32x32x16_bf16 v[96:111], v[144:147], v[148:151], v[96:111]
	v_mfma_f32_32x32x16_bf16 v[96:111], v[10:13], v[148:151], v[96:111]
	v_mfma_f32_32x32x16_bf16 v[80:95], v[6:9], v[152:155], v[80:95]
	ds_read_b64_tr_b16 v[148:149], v14 offset:0x200
	ds_read_b64_tr_b16 v[150:151], v14 offset:0xa00
	ds_read_b64_tr_b16 v[152:153], v14 offset:0x1200
	ds_read_b64_tr_b16 v[154:155], v14 offset:0x1a00
	v_mfma_f32_32x32x16_bf16 v[80:95], v[2:5], v[156:159], v[80:95]
	ds_read_b64_tr_b16 v[156:157], v14 offset:0x2200
	ds_read_b64_tr_b16 v[158:159], v14 offset:0x2a00
	v_mfma_f32_32x32x16_bf16 v[80:95], v[144:147], v[192:195], v[80:95]
	ds_read_b64_tr_b16 v[192:193], v14 offset:0x3200
	ds_read_b64_tr_b16 v[194:195], v14 offset:0x3a00
	s_waitcnt lgkmcnt(0)
	v_mfma_f32_32x32x16_bf16 v[80:95], v[10:13], v[196:199], v[80:95]
	v_mfma_f32_32x32x16_bf16 v[64:79], v[6:9], v[148:151], v[64:79]
	ds_read_b64_tr_b16 v[148:149], v14 offset:0x400
	ds_read_b64_tr_b16 v[150:151], v14 offset:0xc00
	v_mfma_f32_32x32x16_bf16 v[64:79], v[2:5], v[152:155], v[64:79]
	ds_read_b64_tr_b16 v[152:153], v14 offset:0x1400
	ds_read_b64_tr_b16 v[154:155], v14 offset:0x1c00
	v_mfma_f32_32x32x16_bf16 v[64:79], v[144:147], v[156:159], v[64:79]
	ds_read_b64_tr_b16 v[156:157], v14 offset:0x2400
	ds_read_b64_tr_b16 v[158:159], v14 offset:0x2c00
	v_mfma_f32_32x32x16_bf16 v[64:79], v[10:13], v[192:195], v[64:79]
	ds_read_b64_tr_b16 v[192:193], v14 offset:0x3400
	ds_read_b64_tr_b16 v[194:195], v14 offset:0x3c00
	s_waitcnt lgkmcnt(0)
; #define SBAR() __builtin_amdgcn_sched_barrier(0)
; template <int D0> __device__ __forceinline__ void pv_one(f32x16& od, int vb, bf16x8 pa0, bf16x8 pa1, bf16x8 pa2, bf16x8 pa3) {
;     const s16x4 l0 = tr_read<v_rd_off(D0, 0, 0)>(vb), h0 = tr_read<v_rd_off(D0, 0, 1)>(vb), l1 = tr_read<v_rd_off(D0, 1, 0)>(vb), h1 = tr_read<v_rd_off(D0, 1, 1)>(vb);
;     const s16x4 l2 = tr_read<v_rd_off(D0, 2, 0)>(vb), h2 = tr_read<v_rd_off(D0, 2, 1)>(vb), l3 = tr_read<v_rd_off(D0, 3, 0)>(vb), h3 = tr_read<v_rd_off(D0, 3, 1)>(vb);
;     asm volatile("s_waitcnt lgkmcnt(0)" ::: "memory"); SBAR();
;     ...
;     od = __builtin_amdgcn_mfma_f32_32x32x16_bf16(pa0, PK(l0, h0), od, 0, 0, 0);
;     od = __builtin_amdgcn_mfma_f32_32x32x16_bf16(pa1, PK(l1, h1), od, 0, 0, 0);
;     od = __builtin_amdgcn_mfma_f32_32x32x16_bf16(pa2, PK(l2, h2), od, 0, 0, 0);
;     od = __builtin_amdgcn_mfma_f32_32x32x16_bf16(pa3, PK(l3, h3), od, 0, 0, 0);
;     ...
; }
; template <bool RSM> __device__ __forceinline__ void pv_d0(f32x16* o, f32x16& lacc, int vb, bf16x8 pa0, bf16x8 pa1, bf16x8 pa2, bf16x8 pa3) {
;     if (RSM) {
;         const bf16x8 ones = {0x3F80, 0x3F80, 0x3F80, 0x3F80, 0x3F80, 0x3F80, 0x3F80, 0x3F80};
;         lacc = __builtin_amdgcn_mfma_f32_32x32x16_bf16(pa0, ones, lacc, 0, 0, 0);
;         lacc = __builtin_amdgcn_mfma_f32_32x32x16_bf16(pa1, ones, lacc, 0, 0, 0);
;         lacc = __builtin_amdgcn_mfma_f32_32x32x16_bf16(pa2, ones, lacc, 0, 0, 0);
;         lacc = __builtin_amdgcn_mfma_f32_32x32x16_bf16(pa3, ones, lacc, 0, 0, 0); }
;     pv_one<0>(o[0], vb, pa0, pa1, pa2, pa3); pv_one<1>(o[1], vb, pa0, pa1, pa2, pa3); pv_one<2>(o[2], vb, pa0, pa1, pa2, pa3); pv_one<3>(o[3], vb, pa0, pa1, pa2, pa3);
; }
	v_mfma_f32_32x32x16_bf16 v[48:63], v[6:9], v[148:151], v[48:63]
	ds_read_b64_tr_b16 v[148:149], v14 offset:0x600
	ds_read_b64_tr_b16 v[150:151], v14 offset:0xe00
	v_mfma_f32_32x32x16_bf16 v[48:63], v[2:5], v[152:155], v[48:63]
	ds_read_b64_tr_b16 v[152:153], v14 offset:0x1600
	ds_read_b64_tr_b16 v[154:155], v14 offset:0x1e00
	v_mfma_f32_32x32x16_bf16 v[48:63], v[144:147], v[156:159], v[48:63]
	ds_read_b64_tr_b16 v[156:157], v14 offset:0x2600
	ds_read_b64_tr_b16 v[158:159], v14 offset:0x2e00
	v_mfma_f32_32x32x16_bf16 v[48:63], v[10:13], v[192:195], v[48:63]
	ds_read_b64_tr_b16 v[192:193], v14 offset:0x3600
	ds_read_b64_tr_b16 v[194:195], v14 offset:0x3e00
	s_waitcnt lgkmcnt(0)
	v_mfma_f32_32x32x16_bf16 v[32:47], v[6:9], v[148:151], v[32:47]
	s_and_b64 vcc, exec, s[0:1]
	v_mfma_f32_32x32x16_bf16 v[32:47], v[2:5], v[152:155], v[32:47]
	v_mfma_f32_32x32x16_bf16 v[32:47], v[144:147], v[156:159], v[32:47]
	v_mfma_f32_32x32x16_bf16 v[32:47], v[10:13], v[192:195], v[32:47]
	s_setprio 0
	global_load_lds_dwordx4 v[214:215], off
	v_lshl_add_u64 v[214:215], v[214:215], 0, s[74:75]
	s_mov_b32 m0, s22
	s_nop 0
	global_load_lds_dwordx4 v[212:213], off
	v_lshl_add_u64 v[212:213], v[212:213], 0, s[74:75]
	s_add_i32 m0, s22, 0x2000
	s_nop 0
	global_load_lds_dwordx4 v[216:217], off
	v_lshl_add_u64 v[216:217], v[216:217], 0, s[74:75]
	s_cbranch_vccnz .LBB0_724
	s_branch .Lmy_r2ft_1
.Lmy_r2d_2:
	s_setprio 1
	s_mov_b32 s38, s36
	s_mov_b32 s39, s36
	s_mov_b32 s37, s36
	v_mov_b64_e32 v[118:119], s[38:39]
	v_mov_b64_e32 v[116:117], s[36:37]
	s_lshl_b32 s15, s18, 14
	v_add_u32_e32 v0, s15, v192
	v_mfma_f32_32x32x16_bf16 v[80:95], v[6:9], v[116:119], v[80:95]
	ds_read_b64_tr_b16 v[120:121], v0 offset:0
	ds_read_b64_tr_b16 v[122:123], v0 offset:0x800
	ds_read_b64_tr_b16 v[124:125], v0 offset:0x1000
	ds_read_b64_tr_b16 v[126:127], v0 offset:0x1800
	ds_read_b64_tr_b16 v[176:177], v0 offset:0x2000
	ds_read_b64_tr_b16 v[178:179], v0 offset:0x2800
	ds_read_b64_tr_b16 v[180:181], v0 offset:0x3000
	v_mfma_f32_32x32x16_bf16 v[80:95], v[2:5], v[116:119], v[80:95]
	ds_read_b64_tr_b16 v[182:183], v0 offset:0x3800
	s_waitcnt lgkmcnt(0)
	v_mfma_f32_32x32x16_bf16 v[80:95], v[112:115], v[116:119], v[80:95]
	v_mfma_f32_32x32x16_bf16 v[80:95], v[10:13], v[116:119], v[80:95]
	v_mfma_f32_32x32x16_bf16 v[64:79], v[6:9], v[120:123], v[64:79]
	ds_read_b64_tr_b16 v[116:117], v0 offset:0x200
	ds_read_b64_tr_b16 v[118:119], v0 offset:0xa00
	ds_read_b64_tr_b16 v[120:121], v0 offset:0x1200
	ds_read_b64_tr_b16 v[122:123], v0 offset:0x1a00
	v_mfma_f32_32x32x16_bf16 v[64:79], v[2:5], v[124:127], v[64:79]
	ds_read_b64_tr_b16 v[124:125], v0 offset:0x2200
	ds_read_b64_tr_b16 v[126:127], v0 offset:0x2a00
	v_mfma_f32_32x32x16_bf16 v[64:79], v[112:115], v[176:179], v[64:79]
	ds_read_b64_tr_b16 v[176:177], v0 offset:0x3200
	ds_read_b64_tr_b16 v[178:179], v0 offset:0x3a00
	s_waitcnt lgkmcnt(0)
	v_mfma_f32_32x32x16_bf16 v[64:79], v[10:13], v[180:183], v[64:79]
	v_mfma_f32_32x32x16_bf16 v[48:63], v[6:9], v[116:119], v[48:63]
	ds_read_b64_tr_b16 v[116:117], v0 offset:0x400
	ds_read_b64_tr_b16 v[118:119], v0 offset:0xc00
	v_mfma_f32_32x32x16_bf16 v[48:63], v[2:5], v[120:123], v[48:63]
	ds_read_b64_tr_b16 v[120:121], v0 offset:0x1400
	ds_read_b64_tr_b16 v[122:123], v0 offset:0x1c00
	v_mfma_f32_32x32x16_bf16 v[48:63], v[112:115], v[124:127], v[48:63]
	ds_read_b64_tr_b16 v[124:125], v0 offset:0x2400
	ds_read_b64_tr_b16 v[126:127], v0 offset:0x2c00
	v_mfma_f32_32x32x16_bf16 v[48:63], v[10:13], v[176:179], v[48:63]
	ds_read_b64_tr_b16 v[176:177], v0 offset:0x3400
	ds_read_b64_tr_b16 v[178:179], v0 offset:0x3c00
	s_waitcnt lgkmcnt(0)
	v_mfma_f32_32x32x16_bf16 v[32:47], v[6:9], v[116:119], v[32:47]
	ds_read_b64_tr_b16 v[116:117], v0 offset:0x600
	ds_read_b64_tr_b16 v[118:119], v0 offset:0xe00
	v_mfma_f32_32x32x16_bf16 v[32:47], v[2:5], v[120:123], v[32:47]
	ds_read_b64_tr_b16 v[120:121], v0 offset:0x1600
	ds_read_b64_tr_b16 v[122:123], v0 offset:0x1e00
	v_mfma_f32_32x32x16_bf16 v[32:47], v[112:115], v[124:127], v[32:47]
	ds_read_b64_tr_b16 v[124:125], v0 offset:0x2600
	ds_read_b64_tr_b16 v[126:127], v0 offset:0x2e00
	v_mfma_f32_32x32x16_bf16 v[32:47], v[10:13], v[176:179], v[32:47]
	ds_read_b64_tr_b16 v[176:177], v0 offset:0x3600
	ds_read_b64_tr_b16 v[178:179], v0 offset:0x3e00
	s_waitcnt lgkmcnt(0)
	v_mfma_f32_32x32x16_bf16 v[16:31], v[6:9], v[116:119], v[16:31]
	s_and_b64 vcc, exec, s[0:1]
	v_mfma_f32_32x32x16_bf16 v[16:31], v[2:5], v[120:123], v[16:31]
	v_mfma_f32_32x32x16_bf16 v[16:31], v[112:115], v[124:127], v[16:31]
	v_mfma_f32_32x32x16_bf16 v[16:31], v[10:13], v[176:179], v[16:31]
	s_setprio 0
	global_load_lds_dwordx4 v[184:185], off
	v_lshl_add_u64 v[184:185], v[184:185], 0, s[74:75]
	s_mov_b32 m0, s12
	s_nop 0
	global_load_lds_dwordx4 v[186:187], off
	v_lshl_add_u64 v[186:187], v[186:187], 0, s[74:75]
	s_add_i32 m0, s12, 0x2000
	s_nop 0
	global_load_lds_dwordx4 v[188:189], off
	v_lshl_add_u64 v[188:189], v[188:189], 0, s[74:75]
	s_cbranch_vccnz .LBB0_784
	s_branch .Lmy_r2ft_2
; #define SBAR() __builtin_amdgcn_sched_barrier(0)
; template <int D0> __device__ __forceinline__ void pv_one(f32x16& od, int vb, bf16x8 pa0, bf16x8 pa1, bf16x8 pa2, bf16x8 pa3) {
;     const s16x4 l0 = tr_read<v_rd_off(D0, 0, 0)>(vb), h0 = tr_read<v_rd_off(D0, 0, 1)>(vb), l1 = tr_read<v_rd_off(D0, 1, 0)>(vb), h1 = tr_read<v_rd_off(D0, 1, 1)>(vb);
;     const s16x4 l2 = tr_read<v_rd_off(D0, 2, 0)>(vb), h2 = tr_read<v_rd_off(D0, 2, 1)>(vb), l3 = tr_read<v_rd_off(D0, 3, 0)>(vb), h3 = tr_read<v_rd_off(D0, 3, 1)>(vb);
;     asm volatile("s_waitcnt lgkmcnt(0)" ::: "memory"); SBAR();
;     ...
;     od = __builtin_amdgcn_mfma_f32_32x32x16_bf16(pa0, PK(l0, h0), od, 0, 0, 0);
;     od = __builtin_amdgcn_mfma_f32_32x32x16_bf16(pa1, PK(l1, h1), od, 0, 0, 0);
;     od = __builtin_amdgcn_mfma_f32_32x32x16_bf16(pa2, PK(l2, h2), od, 0, 0, 0);
;     od = __builtin_amdgcn_mfma_f32_32x32x16_bf16(pa3, PK(l3, h3), od, 0, 0, 0);
;     ...
; }
; template <bool RSM> __device__ __forceinline__ void pv_d0(f32x16* o, f32x16& lacc, int vb, bf16x8 pa0, bf16x8 pa1, bf16x8 pa2, bf16x8 pa3) {
;     if (RSM) {
;         const bf16x8 ones = {0x3F80, 0x3F80, 0x3F80, 0x3F80, 0x3F80, 0x3F80, 0x3F80, 0x3F80};
;         lacc = __builtin_amdgcn_mfma_f32_32x32x16_bf16(pa0, ones, lacc, 0, 0, 0);
;         lacc = __builtin_amdgcn_mfma_f32_32x32x16_bf16(pa1, ones, lacc, 0, 0, 0);
;         lacc = __builtin_amdgcn_mfma_f32_32x32x16_bf16(pa2, ones, lacc, 0, 0, 0);
;         lacc = __builtin_amdgcn_mfma_f32_32x32x16_bf16(pa3, ones, lacc, 0, 0, 0); }
;     pv_one<0>(o[0], vb, pa0, pa1, pa2, pa3); pv_one<1>(o[1], vb, pa0, pa1, pa2, pa3); pv_one<2>(o[2], vb, pa0, pa1, pa2, pa3); pv_one<3>(o[3], vb, pa0, pa1, pa2, pa3);
; }
.Lmy_r2d_3:
	s_setprio 1
	s_mov_b32 s38, s36
	s_mov_b32 s39, s36
	s_mov_b32 s37, s36
	v_mov_b64_e32 v[134:135], s[38:39]
	v_mov_b64_e32 v[132:133], s[36:37]
	s_lshl_b32 s31, s18, 14
	v_add_u32_e32 v14, s31, v192
	v_mfma_f32_32x32x16_bf16 v[80:95], v[6:9], v[132:135], v[80:95]
	ds_read_b64_tr_b16 v[136:137], v14 offset:0
	ds_read_b64_tr_b16 v[138:139], v14 offset:0x800
	ds_read_b64_tr_b16 v[140:141], v14 offset:0x1000
	ds_read_b64_tr_b16 v[142:143], v14 offset:0x1800
	ds_read_b64_tr_b16 v[176:177], v14 offset:0x2000
	ds_read_b64_tr_b16 v[178:179], v14 offset:0x2800
	ds_read_b64_tr_b16 v[180:181], v14 offset:0x3000
	v_mfma_f32_32x32x16_bf16 v[80:95], v[2:5], v[132:135], v[80:95]
	ds_read_b64_tr_b16 v[182:183], v14 offset:0x3800
	s_waitcnt lgkmcnt(0)
	v_mfma_f32_32x32x16_bf16 v[80:95], v[128:131], v[132:135], v[80:95]
	v_mfma_f32_32x32x16_bf16 v[80:95], v[10:13], v[132:135], v[80:95]
	v_mfma_f32_32x32x16_bf16 v[64:79], v[6:9], v[136:139], v[64:79]
	ds_read_b64_tr_b16 v[132:133], v14 offset:0x200
	ds_read_b64_tr_b16 v[134:135], v14 offset:0xa00
	ds_read_b64_tr_b16 v[136:137], v14 offset:0x1200
	ds_read_b64_tr_b16 v[138:139], v14 offset:0x1a00
	v_mfma_f32_32x32x16_bf16 v[64:79], v[2:5], v[140:143], v[64:79]
	ds_read_b64_tr_b16 v[140:141], v14 offset:0x2200
	ds_read_b64_tr_b16 v[142:143], v14 offset:0x2a00
	v_mfma_f32_32x32x16_bf16 v[64:79], v[128:131], v[176:179], v[64:79]
	ds_read_b64_tr_b16 v[176:177], v14 offset:0x3200
	ds_read_b64_tr_b16 v[178:179], v14 offset:0x3a00
	s_waitcnt lgkmcnt(0)
	v_mfma_f32_32x32x16_bf16 v[64:79], v[10:13], v[180:183], v[64:79]
	v_mfma_f32_32x32x16_bf16 v[48:63], v[6:9], v[132:135], v[48:63]
	ds_read_b64_tr_b16 v[132:133], v14 offset:0x400
	ds_read_b64_tr_b16 v[134:135], v14 offset:0xc00
	v_mfma_f32_32x32x16_bf16 v[48:63], v[2:5], v[136:139], v[48:63]
	ds_read_b64_tr_b16 v[136:137], v14 offset:0x1400
	ds_read_b64_tr_b16 v[138:139], v14 offset:0x1c00
	v_mfma_f32_32x32x16_bf16 v[48:63], v[128:131], v[140:143], v[48:63]
	ds_read_b64_tr_b16 v[140:141], v14 offset:0x2400
	ds_read_b64_tr_b16 v[142:143], v14 offset:0x2c00
	v_mfma_f32_32x32x16_bf16 v[48:63], v[10:13], v[176:179], v[48:63]
	ds_read_b64_tr_b16 v[176:177], v14 offset:0x3400
	ds_read_b64_tr_b16 v[178:179], v14 offset:0x3c00
	s_waitcnt lgkmcnt(0)
	v_mfma_f32_32x32x16_bf16 v[32:47], v[6:9], v[132:135], v[32:47]
	ds_read_b64_tr_b16 v[132:133], v14 offset:0x600
	ds_read_b64_tr_b16 v[134:135], v14 offset:0xe00
	v_mfma_f32_32x32x16_bf16 v[32:47], v[2:5], v[136:139], v[32:47]
	ds_read_b64_tr_b16 v[136:137], v14 offset:0x1600
	ds_read_b64_tr_b16 v[138:139], v14 offset:0x1e00
	v_mfma_f32_32x32x16_bf16 v[32:47], v[128:131], v[140:143], v[32:47]
	ds_read_b64_tr_b16 v[140:141], v14 offset:0x2600
	ds_read_b64_tr_b16 v[142:143], v14 offset:0x2e00
	v_mfma_f32_32x32x16_bf16 v[32:47], v[10:13], v[176:179], v[32:47]
	ds_read_b64_tr_b16 v[176:177], v14 offset:0x3600
	ds_read_b64_tr_b16 v[178:179], v14 offset:0x3e00
	s_waitcnt lgkmcnt(0)
	v_mfma_f32_32x32x16_bf16 v[16:31], v[6:9], v[132:135], v[16:31]
	s_and_b64 vcc, exec, s[0:1]
	v_mfma_f32_32x32x16_bf16 v[16:31], v[2:5], v[136:139], v[16:31]
	v_mfma_f32_32x32x16_bf16 v[16:31], v[128:131], v[140:143], v[16:31]
	v_mfma_f32_32x32x16_bf16 v[16:31], v[10:13], v[176:179], v[16:31]
	s_setprio 0
	global_load_lds_dwordx4 v[184:185], off
	v_lshl_add_u64 v[184:185], v[184:185], 0, s[74:75]
	s_mov_b32 m0, s14
	s_nop 0
	global_load_lds_dwordx4 v[186:187], off
	v_lshl_add_u64 v[186:187], v[186:187], 0, s[74:75]
	s_add_i32 m0, s14, 0x2000
	s_nop 0
	global_load_lds_dwordx4 v[188:189], off
	v_lshl_add_u64 v[188:189], v[188:189], 0, s[74:75]
	s_cbranch_vccnz .LBB0_799
	s_branch .Lmy_r2ft_3
